# S5 scan input projection on f32 matrix cores (v_mfma_f32_16x16x4_f32) + LDS transpose, recurrence as 4 v_fma per step
# speedup vs baseline: 1.0710x; 1.0028x over previous
; __device__ __forceinline__ void s5_task(const Params& p, int l, int task, char* smem) {
;     ...
;   const int li = (l * 2 + dir) * 16 + g;
;   const float lr = p.in[15][li * 64 + lane], lim = p.in[16][li * 64 + lane];
;   const float st = expf(p.in[17][li]);
;   const float mag = expf(lr * st);
;   float sn, cs;
;   sincosf(lim * st, &sn, &cs);
;   const float are = mag * cs, aim = mag * sn;
;   const float den = lr * lr + lim * lim, nre = are - 1.f;
;   const float cre = (nre * lr + aim * lim) / den, cim = (aim * lr - nre * lim) / den;
;   f32x2 bb[16];
;   {
;     const float* br = p.in[18] + ((size_t)(l * 16 + g) * 64 + lane) * 16;
;     const float* bi = p.in[19] + ((size_t)(l * 16 + g) * 64 + lane) * 16;
; #pragma unroll
;     for (int h = 0; h < 16; ++h) {
;       const float r_ = br[h], i_ = bi[h];
;       bb[h] = mk2(cre * r_ - cim * i_, cre * i_ + cim * r_);
;     }
;   }
.LBB0_128:
	s_or_b64 exec, exec, s[40:41]
	s_movk_i32 s40, 0x2200
	v_mul_lo_u32 v76, v2, s40
	v_mul_f32_e32 v2, v54, v5
	v_mul_f32_e32 v5, 0x3fb8aa3b, v2
	s_mov_b32 s2, 0x3fb8aa3b
	v_fma_f32 v7, v2, s2, -v5
	v_rndne_f32_e32 v8, v5
	v_fmac_f32_e32 v7, 0x32a5705f, v2
	v_sub_f32_e32 v5, v5, v8
	v_add_f32_e32 v5, v5, v7
	v_exp_f32_e32 v5, v5
	v_cvt_i32_f32_e32 v7, v8
	s_mov_b32 s2, 0xc2ce8ed0
	v_cmp_ngt_f32_e32 vcc, s2, v2
	s_mov_b32 s2, 0x42b17218
	v_ldexp_f32 v5, v5, v7
	v_cndmask_b32_e32 v5, 0, v5, vcc
	v_cmp_nlt_f32_e32 vcc, s2, v2
	v_xor_b32_e32 v4, v4, v3
	s_brev_b32 s40, 1
	v_cndmask_b32_e32 v2, v181, v5, vcc
	v_mul_f32_e32 v5, v0, v0
	v_fmamk_f32 v7, v5, 0xb94c1982, v175
	v_fmaak_f32 v7, v5, v7, 0xbe2aaa9d
	v_mul_f32_e32 v7, v5, v7
	v_fmac_f32_e32 v0, v0, v7
	v_fmamk_f32 v7, v5, 0x37d75334, v176
	v_fmaak_f32 v7, v5, v7, 0x3d2aabf7
	v_fmaak_f32 v7, v5, v7, 0xbf000004
	v_fma_f32 v5, v5, v7, 1.0
	v_lshlrev_b32_e32 v7, 30, v6
	v_and_b32_e32 v6, 1, v6
	v_cmp_eq_u32_e32 vcc, 0, v6
	v_and_b32_e32 v8, 0x80000000, v7
	v_readlane_b32 s2, v250, 37
	v_cndmask_b32_e32 v6, v5, v0, vcc
	v_xor_b32_e32 v0, 0x80000000, v0
	v_cndmask_b32_e32 v0, v0, v5, vcc
	v_xor_b32_e32 v4, v4, v6
	v_bitop3_b32 v0, v0, v7, s40 bitop3:0x78
	s_movk_i32 s40, 0x1f8
	v_xor_b32_e32 v4, v4, v8
	v_cmp_class_f32_e64 vcc, v3, s40
	s_load_dwordx16 s[44:59], s[0:1], 0x58
	s_waitcnt lgkmcnt(0)
	s_load_dwordx8 s[44:51], s[0:1], 0x98
	v_cndmask_b32_e32 v0, v184, v0, vcc
	v_cndmask_b32_e32 v3, v184, v4, vcc
	v_mul_f32_e32 v50, v2, v0
	v_mul_f32_e32 v53, v2, v3
	v_fma_f32 v52, v2, v0, -1.0
	v_add_u32_e32 v2, s2, v69
	v_ashrrev_i32_e32 v3, 31, v2
	v_lshlrev_b64 v[2:3], 10, v[2:3]
	v_and_b32_e32 v75, 15, v68
	v_lshl_or_b32 v4, v74, 4, v2
	v_mov_b32_e32 v5, v3
	v_lshlrev_b64 v[4:5], 2, v[4:5]
	v_lshl_or_b32 v2, v75, 6, v2
	v_lshrrev_b32_e32 v0, 2, v68
	v_lshl_add_u64 v[6:7], s[58:59], 0, v[4:5]
	s_waitcnt lgkmcnt(0)
	v_lshl_add_u64 v[4:5], s[44:45], 0, v[4:5]
	v_lshlrev_b64 v[2:3], 2, v[2:3]
	v_and_b32_e32 v70, 12, v0
	global_load_dwordx4 v[18:21], v[6:7], off offset:48
	global_load_dwordx4 v[26:29], v[6:7], off offset:32
	global_load_dwordx4 v[34:37], v[6:7], off offset:16
	global_load_dwordx4 v[42:45], v[6:7], off
	global_load_dwordx4 v[22:25], v[4:5], off offset:48
	global_load_dwordx4 v[30:33], v[4:5], off offset:32
	global_load_dwordx4 v[38:41], v[4:5], off offset:16
	global_load_dwordx4 v[46:49], v[4:5], off
	v_lshl_add_u64 v[4:5], s[46:47], 0, v[2:3]
	v_lshl_add_u64 v[6:7], s[48:49], 0, v[2:3]
	v_lshlrev_b32_e32 v0, 2, v70
	v_lshl_add_u64 v[58:59], v[4:5], 0, v[0:1]
	v_lshl_add_u64 v[60:61], v[6:7], 0, v[0:1]
	global_load_dwordx4 v[2:5], v[58:59], off
	global_load_dwordx4 v[6:9], v[60:61], off
	v_mov_b32_e32 v0, v55
	v_pk_mul_f32 v[56:57], v[54:55], v[54:55]
	s_lshr_b32 s43, s30, 3
	v_pk_add_f32 v[56:57], v[56:57], v[56:57] op_sel:[0,1] op_sel_hi:[0,1]
	s_cmp_eq_u32 s31, 0
	s_mul_i32 s98, s31, 0x1200000
	v_lshl_add_u64 v[66:67], v[90:91], 0, s[98:99]
	s_movk_i32 s2, 0x110
	s_mov_b64 s[30:31], 0x1aca0000
	v_lshl_add_u32 v77, v74, 6, v76
	v_mad_u32_u24 v71, v75, s2, v76
	s_mov_b32 s42, 0
	v_readlane_b32 s2, v251, 0
	v_readlane_b32 s38, v250, 23
	v_readlane_b32 s39, v250, 24
	s_waitcnt vmcnt(0)
	v_cvt_pk_bf16_f32 v5, v5, -v9
	v_cvt_pk_bf16_f32 v4, v4, -v8
	v_cvt_pk_bf16_f32 v3, v3, -v7
	v_cvt_pk_bf16_f32 v2, v2, -v6
	global_load_dwordx4 v[6:9], v[58:59], off offset:64
	global_load_dwordx4 v[10:13], v[60:61], off offset:64
	s_waitcnt vmcnt(0)
	v_cvt_pk_bf16_f32 v9, v9, -v13
	v_cvt_pk_bf16_f32 v8, v8, -v12
	v_cvt_pk_bf16_f32 v7, v7, -v11
	v_cvt_pk_bf16_f32 v6, v6, -v10
	global_load_dwordx4 v[10:13], v[58:59], off offset:128
	global_load_dwordx4 v[14:17], v[60:61], off offset:128
	s_waitcnt vmcnt(0)
	v_cvt_pk_bf16_f32 v13, v13, -v17
	v_cvt_pk_bf16_f32 v12, v12, -v16
	v_cvt_pk_bf16_f32 v11, v11, -v15
	v_cvt_pk_bf16_f32 v10, v10, -v14
	global_load_dwordx4 v[14:17], v[58:59], off offset:192
	s_nop 0
	global_load_dwordx4 v[58:61], v[60:61], off offset:192
	s_waitcnt vmcnt(0)
	v_cvt_pk_bf16_f32 v15, v15, -v59
	v_cvt_pk_bf16_f32 v14, v14, -v58
	v_pk_mul_f32 v[58:59], v[0:1], v[52:53] op_sel:[0,1] op_sel_hi:[0,0]
	v_cvt_pk_bf16_f32 v17, v17, -v61
	v_cvt_pk_bf16_f32 v16, v16, -v60
	v_pk_fma_f32 v[60:61], v[54:55], v[52:53], v[58:59]
	v_pk_fma_f32 v[54:55], v[54:55], v[52:53], v[58:59] op_sel_hi:[0,1,1] neg_lo:[0,0,1] neg_hi:[0,0,1]
	v_div_scale_f32 v0, s[40:41], v57, v57, v55
	v_rcp_f32_e32 v51, v0
	s_nop 0
	v_fma_f32 v52, -v0, v51, 1.0
	v_fmac_f32_e32 v51, v52, v51
	v_div_scale_f32 v52, vcc, v55, v57, v55
	v_mul_f32_e32 v54, v52, v51
	v_fma_f32 v58, -v0, v54, v52
	v_fmac_f32_e32 v54, v58, v51
	v_fma_f32 v0, -v0, v54, v52
	v_div_fmas_f32 v0, v0, v51, v54
	v_div_fixup_f32 v73, v0, v57, v55
	v_div_scale_f32 v0, s[40:41], v56, v56, v60
	v_rcp_f32_e32 v51, v0
	s_cselect_b64 s[40:41], -1, 0
	s_lshl_b32 s44, s43, 8
	s_add_i32 s44, s44, 0x8000
	v_fma_f32 v52, -v0, v51, 1.0
	v_fmac_f32_e32 v51, v52, v51
	v_div_scale_f32 v52, vcc, v60, v56, v60
	v_mul_f32_e32 v54, v52, v51
	v_fma_f32 v55, -v0, v54, v52
	v_fmac_f32_e32 v54, v55, v51
	v_fma_f32 v0, -v0, v54, v52
	v_div_fmas_f32 v0, v0, v51, v54
	v_div_fixup_f32 v72, v0, v56, v60
	v_pk_mul_f32 v[56:57], v[46:47], v[72:73] op_sel:[0,1] op_sel_hi:[0,0]
	v_pk_fma_f32 v[54:55], v[42:43], v[72:73], v[56:57] neg_lo:[0,0,1] neg_hi:[0,0,1]
	v_pk_fma_f32 v[56:57], v[42:43], v[72:73], v[56:57] op_sel_hi:[0,1,1]
	v_mov_b32_e32 v55, v57
	v_pk_mul_f32 v[56:57], v[46:47], v[72:73] op_sel:[1,1] op_sel_hi:[1,0]
	v_mov_b32_e32 v0, v43
	v_pk_fma_f32 v[46:47], v[0:1], v[72:73], v[56:57] neg_lo:[0,0,1] neg_hi:[0,0,1]
	v_pk_fma_f32 v[42:43], v[42:43], v[72:73], v[56:57] op_sel:[1,0,0]
; __device__ __forceinline__ void s5_task(const Params& p, int l, int task, char* smem) {
;     ...
;   f32x2 bb[16];
;   {
;     const float* br = p.in[18] + ((size_t)(l * 16 + g) * 64 + lane) * 16;
;     const float* bi = p.in[19] + ((size_t)(l * 16 + g) * 64 + lane) * 16;
; #pragma unroll
;     for (int h = 0; h < 16; ++h) {
;       const float r_ = br[h], i_ = bi[h];
;       bb[h] = mk2(cre * r_ - cim * i_, cre * i_ + cim * r_);
;     }
;   }
	v_pk_mul_f32 v[56:57], v[48:49], v[72:73] op_sel:[0,1] op_sel_hi:[0,0]
	v_mov_b32_e32 v0, v49
	v_mov_b32_e32 v47, v43
	v_pk_fma_f32 v[42:43], v[44:45], v[72:73], v[56:57] neg_lo:[0,0,1] neg_hi:[0,0,1]
	v_pk_fma_f32 v[56:57], v[44:45], v[72:73], v[56:57] op_sel_hi:[0,1,1]
	v_pk_mul_f32 v[48:49], v[0:1], v[72:73] op_sel:[0,1] op_sel_hi:[0,0]
	v_mov_b32_e32 v0, v45
	v_mov_b32_e32 v52, v45
	v_mov_b32_e32 v43, v57
	v_pk_fma_f32 v[44:45], v[0:1], v[72:73], v[48:49] neg_lo:[0,0,1] neg_hi:[0,0,1]
	v_pk_fma_f32 v[48:49], v[52:53], v[72:73], v[48:49] op_sel_hi:[0,1,1]
	v_pk_mul_f32 v[56:57], v[38:39], v[72:73] op_sel:[0,1] op_sel_hi:[0,0]
	v_mov_b32_e32 v45, v49
	v_pk_fma_f32 v[48:49], v[34:35], v[72:73], v[56:57] neg_lo:[0,0,1] neg_hi:[0,0,1]
	v_pk_fma_f32 v[56:57], v[34:35], v[72:73], v[56:57] op_sel_hi:[0,1,1]
	v_mov_b32_e32 v49, v57
	v_pk_mul_f32 v[56:57], v[72:73], v[38:39] op_sel:[1,1] op_sel_hi:[0,1]
	v_mov_b32_e32 v0, v35
	v_pk_fma_f32 v[38:39], v[0:1], v[72:73], v[56:57] neg_lo:[0,0,1] neg_hi:[0,0,1]
	v_pk_fma_f32 v[34:35], v[34:35], v[72:73], v[56:57] op_sel:[1,0,0]
	v_pk_mul_f32 v[56:57], v[72:73], v[40:41] op_sel:[1,0] op_sel_hi:[0,0]
	v_mov_b32_e32 v0, v41
	v_mov_b32_e32 v39, v35
	v_pk_fma_f32 v[34:35], v[72:73], v[36:37], v[56:57] neg_lo:[0,0,1] neg_hi:[0,0,1]
	v_pk_fma_f32 v[56:57], v[72:73], v[36:37], v[56:57] op_sel_hi:[1,0,1]
	v_pk_mul_f32 v[40:41], v[72:73], v[0:1] op_sel:[1,0] op_sel_hi:[0,0]
	v_mov_b32_e32 v0, v37
	v_mov_b32_e32 v52, v37
	v_mov_b32_e32 v35, v57
	v_pk_fma_f32 v[36:37], v[72:73], v[0:1], v[40:41] neg_lo:[0,0,1] neg_hi:[0,0,1]
	v_pk_fma_f32 v[40:41], v[72:73], v[52:53], v[40:41] op_sel_hi:[1,0,1]
	v_pk_mul_f32 v[56:57], v[72:73], v[30:31] op_sel:[1,0] op_sel_hi:[0,0]
	v_mov_b32_e32 v37, v41
	v_pk_fma_f32 v[40:41], v[72:73], v[26:27], v[56:57] neg_lo:[0,0,1] neg_hi:[0,0,1]
	v_pk_fma_f32 v[56:57], v[72:73], v[26:27], v[56:57] op_sel_hi:[1,0,1]
	v_mov_b32_e32 v0, v27
	v_mov_b32_e32 v41, v57
	v_pk_mul_f32 v[56:57], v[72:73], v[30:31] op_sel:[1,1] op_sel_hi:[0,1]
	v_pk_fma_f32 v[30:31], v[72:73], v[0:1], v[56:57] neg_lo:[0,0,1] neg_hi:[0,0,1]
	v_pk_fma_f32 v[26:27], v[72:73], v[26:27], v[56:57] op_sel:[0,1,0]
	v_mov_b32_e32 v0, v33
	v_mov_b32_e32 v31, v27
	v_pk_mul_f32 v[26:27], v[72:73], v[32:33] op_sel:[1,0] op_sel_hi:[0,0]
	v_pk_fma_f32 v[56:57], v[72:73], v[28:29], v[26:27] neg_lo:[0,0,1] neg_hi:[0,0,1]
	v_pk_fma_f32 v[26:27], v[72:73], v[28:29], v[26:27] op_sel_hi:[1,0,1]
	v_mov_b32_e32 v28, v29
	v_mov_b32_e32 v57, v27
	v_pk_mul_f32 v[26:27], v[72:73], v[0:1] op_sel:[1,0] op_sel_hi:[0,0]
	v_mov_b32_e32 v0, v29
	v_pk_fma_f32 v[32:33], v[72:73], v[0:1], v[26:27] neg_lo:[0,0,1] neg_hi:[0,0,1]
	v_pk_fma_f32 v[26:27], v[72:73], v[28:29], v[26:27] op_sel_hi:[1,0,1]
	v_mov_b32_e32 v0, v19
	v_mov_b32_e32 v33, v27
	v_pk_mul_f32 v[26:27], v[72:73], v[22:23] op_sel:[1,0] op_sel_hi:[0,0]
	v_pk_mul_f32 v[22:23], v[72:73], v[22:23] op_sel:[1,1] op_sel_hi:[0,1]
	v_pk_fma_f32 v[58:59], v[72:73], v[18:19], v[26:27] neg_lo:[0,0,1] neg_hi:[0,0,1]
	v_pk_fma_f32 v[26:27], v[72:73], v[18:19], v[26:27] op_sel_hi:[1,0,1]
	v_pk_fma_f32 v[60:61], v[72:73], v[0:1], v[22:23] neg_lo:[0,0,1] neg_hi:[0,0,1]
	v_pk_fma_f32 v[18:19], v[72:73], v[18:19], v[22:23] op_sel:[0,1,0]
	v_mov_b32_e32 v0, v21
	v_mov_b32_e32 v61, v19
	v_pk_mul_f32 v[18:19], v[72:73], v[24:25] op_sel:[1,0] op_sel_hi:[0,0]
	v_pk_fma_f32 v[62:63], v[72:73], v[20:21], v[18:19] neg_lo:[0,0,1] neg_hi:[0,0,1]
	v_pk_fma_f32 v[18:19], v[72:73], v[20:21], v[18:19] op_sel_hi:[1,0,1]
	v_mov_b32_e32 v20, v25
	v_mov_b32_e32 v18, v21
	v_pk_mul_f32 v[20:21], v[72:73], v[20:21] op_sel:[1,0] op_sel_hi:[0,0]
	v_pk_fma_f32 v[64:65], v[72:73], v[0:1], v[20:21] neg_lo:[0,0,1] neg_hi:[0,0,1]
; __device__ __forceinline__ bf16_t f2bf(float f) { return (bf16_t)(pack2(f, 0.f) & 0xffffu); }
; __device__ __forceinline__ void s5_task(const Params& p, int l, int task, char* smem) {
;     ...
;   f32x2 bb[16];
;   {
;     const float* br = p.in[18] + ((size_t)(l * 16 + g) * 64 + lane) * 16;
;     const float* bi = p.in[19] + ((size_t)(l * 16 + g) * 64 + lane) * 16;
; #pragma unroll
;     for (int h = 0; h < 16; ++h) {
;       const float r_ = br[h], i_ = bi[h];
;       bb[h] = mk2(cre * r_ - cim * i_, cre * i_ + cim * r_);
;     }
;   }
;   bf16x8 cB[4];
;   {
;     const float* cr = p.in[20] + ((size_t)(l * 16 + g) * 16 + fr) * 64;
;     const float* ci = p.in[21] + ((size_t)(l * 16 + g) * 16 + fr) * 64;
; #pragma unroll
;     for (int ks = 0; ks < 4; ++ks)
; #pragma unroll
;       for (int j = 0; j < 8; ++j) {
;         const int K = 32 * ks + fq * 8 + j, pp = K >> 1;
;         const float val = (K & 1) ? -ci[pp] : cr[pp];
;         cB[ks][j] = (short)f2bf(val);
;       }
;   }
;   f32x2 hh = mk2(0.f, 0.f);
;   const f32x2 are2 = mk2(are, are), aim2 = mk2(-aim, aim);
;   u32x4 r0, r1;
;   {
;     const u32x4* src = (const u32x4*)(P + (size_t)seq_row(b, dir, lane) * PC + C_S5U + g * 16);
;     r0 = src[0]; r1 = src[1];
;   }
	v_xor_b32_e32 v0, 0xff, v74
	v_cndmask_b32_e64 v0, v0, v74, s[40:41]
	v_mov_b32_e32 v63, v19
	v_pk_fma_f32 v[18:19], v[72:73], v[18:19], v[20:21] op_sel_hi:[1,0,1]
	v_or_b32_e32 v0, s44, v0
	v_lshlrev_b32_e32 v20, 4, v69
	v_mul_lo_u32 v0, v0, s74
	v_ashrrev_i32_e32 v21, 31, v20
	v_mov_b32_e32 v59, v27
	v_mov_b32_e32 v65, v19
	v_lshl_add_u64 v[18:19], v[94:95], 0, v[0:1]
	v_lshlrev_b64 v[26:27], 1, v[20:21]
	v_lshl_add_u64 v[22:23], v[18:19], 0, v[26:27]
	global_load_dwordx4 v[18:21], v[22:23], off offset:2096
	s_nop 0
	global_load_dwordx4 v[22:25], v[22:23], off offset:2080
	v_lshl_add_u64 v[28:29], v[66:67], 0, v[26:27]
	v_lshlrev_b32_e32 v0, 1, v70
	v_lshl_add_u64 v[28:29], v[28:29], 0, v[0:1]
	v_and_b32_e32 v72, 48, v68
	v_lshl_add_u64 v[66:67], v[28:29], 0, s[30:31]
	v_mul_i32_i24_e32 v28, 0xffffffc4, v74
	v_mov_b32_e32 v0, v1
	v_mov_b32_e32 v51, v50
	v_xor_b32_e32 v52, 0x80000000, v53
	s_lshl_b32 s45, s43, 11
	v_lshl_add_u64 v[68:69], v[94:95], 0, v[26:27]
	v_add_u32_e32 v78, v77, v28
	v_add_u32_e32 v79, v71, v72
	v_mov_b64_e32 v[70:71], v[0:1]
	ds_write_b32 v78, v54
	ds_write_b32 v78, v55 offset:256
	ds_write_b32 v78, v46 offset:512
	ds_write_b32 v78, v47 offset:768
	ds_write_b32 v78, v42 offset:1024
	ds_write_b32 v78, v43 offset:1280
	ds_write_b32 v78, v44 offset:1536
	ds_write_b32 v78, v45 offset:1792
	ds_write_b32 v78, v48 offset:2048
	ds_write_b32 v78, v49 offset:2304
	ds_write_b32 v78, v38 offset:2560
	ds_write_b32 v78, v39 offset:2816
	ds_write_b32 v78, v34 offset:3072
	ds_write_b32 v78, v35 offset:3328
	ds_write_b32 v78, v36 offset:3584
	ds_write_b32 v78, v37 offset:3840
	ds_write_b32 v78, v40 offset:4096
	ds_write_b32 v78, v41 offset:4352
	ds_write_b32 v78, v30 offset:4608
	ds_write_b32 v78, v31 offset:4864
	ds_write_b32 v78, v56 offset:5120
	ds_write_b32 v78, v57 offset:5376
	ds_write_b32 v78, v32 offset:5632
	ds_write_b32 v78, v33 offset:5888
	ds_write_b32 v78, v58 offset:6144
	ds_write_b32 v78, v59 offset:6400
	ds_write_b32 v78, v60 offset:6656
	ds_write_b32 v78, v61 offset:6912
	ds_write_b32 v78, v62 offset:7168
	ds_write_b32 v78, v63 offset:7424
	ds_write_b32 v78, v64 offset:7680
	ds_write_b32 v78, v65 offset:7936
	v_lshl_add_u32 v0, v72, 5, v76
	v_lshl_add_u32 v0, v75, 2, v0
	ds_read_b32 v30, v0
	ds_read_b32 v31, v0 offset:256
	ds_read_b32 v32, v0 offset:64
	ds_read_b32 v33, v0 offset:320
	ds_read_b32 v34, v0 offset:128
	ds_read_b32 v35, v0 offset:384
	ds_read_b32 v36, v0 offset:192
	ds_read_b32 v37, v0 offset:448
	ds_read_b32 v38, v0 offset:2048
	ds_read_b32 v39, v0 offset:2304
	ds_read_b32 v40, v0 offset:2112
	ds_read_b32 v41, v0 offset:2368
	ds_read_b32 v42, v0 offset:2176
	ds_read_b32 v43, v0 offset:2432
	ds_read_b32 v44, v0 offset:2240
	ds_read_b32 v45, v0 offset:2496
	ds_read_b32 v46, v0 offset:4096
	ds_read_b32 v47, v0 offset:4352
	ds_read_b32 v48, v0 offset:4160
	ds_read_b32 v49, v0 offset:4416
	ds_read_b32 v54, v0 offset:4224
	ds_read_b32 v55, v0 offset:4480
	ds_read_b32 v56, v0 offset:4288
	ds_read_b32 v57, v0 offset:4544
	ds_read_b32 v58, v0 offset:6144
	ds_read_b32 v59, v0 offset:6400
	ds_read_b32 v60, v0 offset:6208
	ds_read_b32 v61, v0 offset:6464
	ds_read_b32 v62, v0 offset:6272
	ds_read_b32 v63, v0 offset:6528
	ds_read_b32 v64, v0 offset:6336
	ds_read_b32 v65, v0 offset:6592
	v_lshrrev_b32_e32 v26, 6, v172
	v_mul_u32_u24_e32 v26, 0x2800, v26
	v_add_u32_e32 v26, 0x8800, v26
	v_mul_u32_u24_e32 v27, 0x50, v75
	v_add3_u32 v245, v26, v27, v72
	v_mul_u32_u24_e32 v28, 0xa0, v72
	v_add3_u32 v246, v26, v27, v28
	v_lshrrev_b32_e32 v28, 2, v72
	v_lshl_add_u32 v244, v75, 6, v76
	v_add_u32_e32 v244, v244, v28
	s_waitcnt lgkmcnt(0)
	s_branch .LBB0_130

; #define S5_LD(t_, U_)  { _Pragma("unroll") for (int i = 0; i < 4; ++i) U_[i] = *(const float4*)(U + (t_) * 16 + i * 4); }
; __device__ __forceinline__ void s5_task(const Params& p, int l, int task, char* smem) {
;     ...
;     for (int sub = 0; sub < 4; ++sub) {
;       float4 uA[4], uB[4];
;       S5_LD(sub * 16, uA);
; #pragma unroll
;       for (int tt = 0; tt < 16; tt += 2) {
;         S5_LD(sub * 16 + tt + 1, uB);
;         S5_STEP(tt, uA);
;         if (tt + 2 < 16) S5_LD(sub * 16 + tt + 2, uA);
;         S5_STEP(tt + 1, uB);
;       }
;       f32x4 y = {0.f, 0.f, 0.f, 0.f};
; #pragma unroll
;       for (int ks = 0; ks < 4; ++ks) {
;         const bf16x8 a = *(const bf16x8*)(Hs + fr * 136 + 32 * ks + fq * 8);
;         y = __builtin_amdgcn_mfma_f32_16x16x32_bf16(cB[ks], a, y, 0, 0, 0);
;       }
.LBB0_134:
	v_lshl_add_u32 v84, s48, 10, v244
	ds_read_b32 v80, v84
	ds_read_b32 v81, v84 offset:16
	ds_read_b32 v82, v84 offset:32
	ds_read_b32 v83, v84 offset:48
	s_waitcnt lgkmcnt(3)
	v_mfma_f32_16x16x4_f32 v[196:199], v80, v30, 0
	v_mfma_f32_16x16x4_f32 v[200:203], v80, v31, 0
	v_mfma_f32_16x16x4_f32 v[204:207], v80, v32, 0
	v_mfma_f32_16x16x4_f32 v[208:211], v80, v33, 0
	v_mfma_f32_16x16x4_f32 v[212:215], v80, v34, 0
	v_mfma_f32_16x16x4_f32 v[216:219], v80, v35, 0
	v_mfma_f32_16x16x4_f32 v[220:223], v80, v36, 0
	v_mfma_f32_16x16x4_f32 v[224:227], v80, v37, 0
	s_waitcnt lgkmcnt(2)
	v_mfma_f32_16x16x4_f32 v[196:199], v81, v38, v[196:199]
	v_mfma_f32_16x16x4_f32 v[200:203], v81, v39, v[200:203]
	v_mfma_f32_16x16x4_f32 v[204:207], v81, v40, v[204:207]
	v_mfma_f32_16x16x4_f32 v[208:211], v81, v41, v[208:211]
	v_mfma_f32_16x16x4_f32 v[212:215], v81, v42, v[212:215]
	v_mfma_f32_16x16x4_f32 v[216:219], v81, v43, v[216:219]
	v_mfma_f32_16x16x4_f32 v[220:223], v81, v44, v[220:223]
	v_mfma_f32_16x16x4_f32 v[224:227], v81, v45, v[224:227]
	s_waitcnt lgkmcnt(1)
	v_mfma_f32_16x16x4_f32 v[196:199], v82, v46, v[196:199]
	v_mfma_f32_16x16x4_f32 v[200:203], v82, v47, v[200:203]
	v_mfma_f32_16x16x4_f32 v[204:207], v82, v48, v[204:207]
	v_mfma_f32_16x16x4_f32 v[208:211], v82, v49, v[208:211]
	v_mfma_f32_16x16x4_f32 v[212:215], v82, v54, v[212:215]
	v_mfma_f32_16x16x4_f32 v[216:219], v82, v55, v[216:219]
	v_mfma_f32_16x16x4_f32 v[220:223], v82, v56, v[220:223]
	v_mfma_f32_16x16x4_f32 v[224:227], v82, v57, v[224:227]
	s_waitcnt lgkmcnt(0)
	v_mfma_f32_16x16x4_f32 v[196:199], v83, v58, v[196:199]
	v_mfma_f32_16x16x4_f32 v[200:203], v83, v59, v[200:203]
	v_mfma_f32_16x16x4_f32 v[204:207], v83, v60, v[204:207]
	v_mfma_f32_16x16x4_f32 v[208:211], v83, v61, v[208:211]
	v_mfma_f32_16x16x4_f32 v[212:215], v83, v62, v[212:215]
	v_mfma_f32_16x16x4_f32 v[216:219], v83, v63, v[216:219]
	v_mfma_f32_16x16x4_f32 v[220:223], v83, v64, v[220:223]
	v_mfma_f32_16x16x4_f32 v[224:227], v83, v65, v[224:227]
	s_nop 7
	s_nop 2
	ds_write_b128 v245, v[196:199]
	ds_write_b128 v245, v[200:203] offset:1280
	ds_write_b128 v245, v[204:207] offset:2560
	ds_write_b128 v245, v[208:211] offset:3840
	ds_write_b128 v245, v[212:215] offset:5120
	ds_write_b128 v245, v[216:219] offset:6400
	ds_write_b128 v245, v[220:223] offset:7680
	ds_write_b128 v245, v[224:227] offset:8960
	ds_read_b128 v[196:199], v246
	ds_read_b128 v[212:215], v246 offset:1280
	ds_read_b128 v[200:203], v246 offset:16
	ds_read_b128 v[216:219], v246 offset:1296
	ds_read_b128 v[204:207], v246 offset:32
	ds_read_b128 v[220:223], v246 offset:1312
	ds_read_b128 v[208:211], v246 offset:48
	ds_read_b128 v[224:227], v246 offset:1328
	s_waitcnt lgkmcnt(6)
	v_fma_f32 v84, v52, v71, v196
	v_fma_f32 v85, v53, v70, v212
	v_fma_f32 v88, v50, v70, v84
	v_fma_f32 v89, v51, v71, v85
	v_cvt_pk_bf16_f32 v86, v88, v89
	ds_write_b32 v78, v86 offset:4096
	v_fma_f32 v84, v52, v89, v197
	v_fma_f32 v85, v53, v88, v213
	v_fma_f32 v70, v50, v88, v84
	v_fma_f32 v71, v51, v89, v85
	v_cvt_pk_bf16_f32 v87, v70, v71
	ds_write_b32 v78, v87 offset:4368
	v_fma_f32 v84, v52, v71, v198
	v_fma_f32 v85, v53, v70, v214
	v_fma_f32 v88, v50, v70, v84
	v_fma_f32 v89, v51, v71, v85
	v_cvt_pk_bf16_f32 v86, v88, v89
	ds_write_b32 v78, v86 offset:4640
	v_fma_f32 v84, v52, v89, v199
	v_fma_f32 v85, v53, v88, v215
	v_fma_f32 v70, v50, v88, v84
	v_fma_f32 v71, v51, v89, v85
	v_cvt_pk_bf16_f32 v87, v70, v71
	ds_write_b32 v78, v87 offset:4912
	s_waitcnt lgkmcnt(8)
	v_fma_f32 v84, v52, v71, v200
	v_fma_f32 v85, v53, v70, v216
	v_fma_f32 v88, v50, v70, v84
	v_fma_f32 v89, v51, v71, v85
	v_cvt_pk_bf16_f32 v86, v88, v89
	ds_write_b32 v78, v86 offset:5184
	v_fma_f32 v84, v52, v89, v201
	v_fma_f32 v85, v53, v88, v217
	v_fma_f32 v70, v50, v88, v84
	v_fma_f32 v71, v51, v89, v85
	v_cvt_pk_bf16_f32 v87, v70, v71
	ds_write_b32 v78, v87 offset:5456
	v_fma_f32 v84, v52, v71, v202
	v_fma_f32 v85, v53, v70, v218
	v_fma_f32 v88, v50, v70, v84
	v_fma_f32 v89, v51, v71, v85
	v_cvt_pk_bf16_f32 v86, v88, v89
	ds_write_b32 v78, v86 offset:5728
	v_fma_f32 v84, v52, v89, v203
	v_fma_f32 v85, v53, v88, v219
	v_fma_f32 v70, v50, v88, v84
	v_fma_f32 v71, v51, v89, v85
	v_cvt_pk_bf16_f32 v87, v70, v71
	ds_write_b32 v78, v87 offset:6000
	s_waitcnt lgkmcnt(10)
	v_fma_f32 v84, v52, v71, v204
	v_fma_f32 v85, v53, v70, v220
	v_fma_f32 v88, v50, v70, v84
	v_fma_f32 v89, v51, v71, v85
	v_cvt_pk_bf16_f32 v86, v88, v89
	ds_write_b32 v78, v86 offset:6272
	v_fma_f32 v84, v52, v89, v205
	v_fma_f32 v85, v53, v88, v221
	v_fma_f32 v70, v50, v88, v84
	v_fma_f32 v71, v51, v89, v85
	v_cvt_pk_bf16_f32 v87, v70, v71
	ds_write_b32 v78, v87 offset:6544
	v_fma_f32 v84, v52, v71, v206
	v_fma_f32 v85, v53, v70, v222
	v_fma_f32 v88, v50, v70, v84
	v_fma_f32 v89, v51, v71, v85
	v_cvt_pk_bf16_f32 v86, v88, v89
	ds_write_b32 v78, v86 offset:6816
	v_fma_f32 v84, v52, v89, v207
	v_fma_f32 v85, v53, v88, v223
	v_fma_f32 v70, v50, v88, v84
	v_fma_f32 v71, v51, v89, v85
	v_cvt_pk_bf16_f32 v87, v70, v71
	ds_write_b32 v78, v87 offset:7088
	s_waitcnt lgkmcnt(12)
	v_fma_f32 v84, v52, v71, v208
	v_fma_f32 v85, v53, v70, v224
	v_fma_f32 v88, v50, v70, v84
	v_fma_f32 v89, v51, v71, v85
	v_cvt_pk_bf16_f32 v86, v88, v89
	ds_write_b32 v78, v86 offset:7360
	v_fma_f32 v84, v52, v89, v209
	v_fma_f32 v85, v53, v88, v225
	v_fma_f32 v70, v50, v88, v84
	v_fma_f32 v71, v51, v89, v85
	v_cvt_pk_bf16_f32 v87, v70, v71
	ds_write_b32 v78, v87 offset:7632
	v_fma_f32 v84, v52, v71, v210
	v_fma_f32 v85, v53, v70, v226
	v_fma_f32 v88, v50, v70, v84
	v_fma_f32 v89, v51, v71, v85
	v_cvt_pk_bf16_f32 v86, v88, v89
	ds_write_b32 v78, v86 offset:7904
	v_fma_f32 v84, v52, v89, v211
	v_fma_f32 v85, v53, v88, v227
	v_fma_f32 v70, v50, v88, v84
	v_fma_f32 v71, v51, v89, v85
	v_cvt_pk_bf16_f32 v87, v70, v71
	ds_write_b32 v78, v87 offset:8176
	s_lshl_b32 s42, s48, 4
	ds_read_b128 v[26:29], v79 offset:4096
	ds_read_b128 v[80:83], v79 offset:4160
	s_waitcnt lgkmcnt(1)
	v_mfma_f32_16x16x32_bf16 v[26:29], v[2:5], v[26:29], 0
	s_add_i32 s42, s42, s47
	v_or_b32_e32 v0, s42, v75
	s_cmpk_gt_u32 s42, 0xff
	s_waitcnt lgkmcnt(0)
	v_mfma_f32_16x16x32_bf16 v[26:29], v[6:9], v[80:83], v[26:29]
	ds_read_b128 v[80:83], v79 offset:4224
	ds_read_b128 v[84:87], v79 offset:4288
	s_mov_b64 s[42:43], -1
	s_waitcnt lgkmcnt(1)
	v_mfma_f32_16x16x32_bf16 v[26:29], v[10:13], v[80:83], v[26:29]
	s_waitcnt lgkmcnt(0)
	v_mfma_f32_16x16x32_bf16 v[26:29], v[14:17], v[84:87], v[26:29]
	s_cbranch_scc0 .LBB0_136
	v_add_u32_e32 v72, 0xffffff00, v0
	v_sub_u32_e32 v73, 0x8ff, v0
	v_cndmask_b32_e64 v72, v73, v72, s[40:41]
	v_add_u32_e32 v72, s45, v72
	s_mov_b64 s[42:43], 0
